# seam 15 XCD-local too and final RMSNorm rows assigned XCD-locally (rows of the row tiles the XCD produced)
# baseline (speedup 1.0000x reference)
.LBB0_1978:
	s_andn2_saveexec_b64 s[8:9], s[8:9]
	s_cbranch_execz .LBB0_1998
	s_waitcnt lgkmcnt(0)
	s_cmp_eq_u32 s99, 0
	s_cbranch_scc1 .Lxl_15
	s_mov_b64 s[8:9], exec
	buffer_wbl2 sc1
	s_waitcnt lgkmcnt(0)
	s_waitcnt vmcnt(0)
	v_mbcnt_lo_u32_b32 v1, s8, 0
	v_mbcnt_hi_u32_b32 v1, s9, v1
	v_cmp_eq_u32_e32 vcc, 0, v1
	s_and_saveexec_b64 s[10:11], vcc
	s_cbranch_execz .LBB0_1981
	s_bcnt1_i32_b64 s8, s[8:9]
	v_mov_b32_e32 v2, 0x303000
	v_mov_b32_e32 v3, s8
	global_atomic_add v2, v2, v3, s[34:35] offset:1024 sc0

.Lxl_15:
	s_mov_b64 s[8:9], exec
	v_mbcnt_lo_u32_b32 v0, s8, 0
	v_mbcnt_hi_u32_b32 v0, s9, v0
	v_cmp_eq_u32_e32 vcc, 0, v0
	s_waitcnt vmcnt(0)
	buffer_inv sc1
	s_and_saveexec_b64 s[10:11], vcc
	s_cbranch_execz .LBB0_1997
	s_bcnt1_i32_b64 s8, s[8:9]
	v_mov_b32_e32 v0, 0x2000
	v_mov_b32_e32 v1, s8
	global_atomic_add v0, v1, s[6:7] offset:1024

.LBB0_1999:
.LBB0_2000:
	s_cmp_lt_i32 s20, 17
	s_cselect_b64 s[4:5], -1, 0
	s_and_b64 s[2:3], s[4:5], s[2:3]
	s_andn2_b64 vcc, exec, s[2:3]
	s_cbranch_vccnz .LBB0_2004
	s_mov_b64 s[2:3], s[0:1]
	s_mov_b64 s[4:5], s[0:1]
	s_cmpk_gt_i32 s28, 0x7fff
	s_cbranch_scc1 .LBB0_2004
	s_load_dwordx2 s[6:7], s[0:1], 0x98
	s_load_dwordx2 s[8:9], s[2:3], 0xa0
	s_load_dwordx2 s[10:11], s[4:5], 0xa8
	s_mov_b32 s98, 0x8000
	s_cmp_lg_u32 s99, 0
	s_cbranch_scc1 .Lfin_map
	s_lshr_b32 s12, s28, 3
	s_and_b32 s12, s12, 7
	s_add_i32 s98, s12, 1
	s_lshl_b32 s98, s98, 12
	s_lshl_b32 s12, s12, 12
	s_lshr_b32 s13, s28, 6
	s_lshl_b32 s13, s13, 3
	s_add_i32 s12, s12, s13
	s_and_b32 s13, s28, 7
	s_add_i32 s28, s12, s13
	s_lshr_b32 s30, s30, 3
.Lfin_map:
	s_ashr_i32 s29, s28, 31
	s_lshl_b64 s[0:1], s[28:29], 2
	v_lshlrev_b32_e32 v0, 4, v242
	v_mov_b32_e32 v1, 0
	s_waitcnt lgkmcnt(0)
	s_add_u32 s0, s10, s0
	s_addc_u32 s1, s11, s1
	s_add_u32 s0, s0, 0x100000
	s_addc_u32 s1, s1, 0
	s_ashr_i32 s31, s30, 31
	s_lshl_b64 s[2:3], s[30:31], 2
	s_lshl_b64 s[4:5], s[28:29], 12
	s_add_u32 s4, s8, s4
	s_addc_u32 s5, s9, s5
	v_lshl_add_u64 v[4:5], s[4:5], 0, v[0:1]
	s_mov_b64 s[4:5], 0x800
	v_lshl_add_u64 v[2:3], s[6:7], 0, v[0:1]
	v_lshl_add_u64 v[4:5], v[4:5], 0, s[4:5]
	s_lshl_b64 s[4:5], s[30:31], 12
	v_mov_b32_e32 v0, 0x358637bd
	global_load_dwordx4 v[20:23], v[2:3], off
	global_load_dwordx4 v[24:27], v[2:3], off offset:1024
	global_load_dwordx4 v[28:31], v[2:3], off offset:2048
	global_load_dwordx4 v[32:35], v[2:3], off offset:3072
	global_load_dword v18, v1, s[0:1]
	global_load_dwordx4 v[36:39], v[4:5], off offset:-2048
	global_load_dwordx4 v[40:43], v[4:5], off offset:-1024
	global_load_dwordx4 v[44:47], v[4:5], off
	global_load_dwordx4 v[48:51], v[4:5], off offset:1024
.Lfin_A:
	v_lshl_add_u64 v[6:7], v[4:5], 0, s[4:5]
	s_add_i32 s28, s28, s30
	s_add_u32 s0, s0, s2
	s_addc_u32 s1, s1, s3
	s_cmp_lt_i32 s28, s98
	s_cbranch_scc0 .Lfin_A_last
	global_load_dword v68, v1, s[0:1]
	global_load_dwordx4 v[52:55], v[6:7], off offset:-2048
	global_load_dwordx4 v[56:59], v[6:7], off offset:-1024
	global_load_dwordx4 v[60:63], v[6:7], off
	global_load_dwordx4 v[64:67], v[6:7], off offset:1024
	s_waitcnt vmcnt(5)
	v_fmamk_f32 v18, v18, 0x3a800000, v0
	v_rsq_f32_e32 v18, v18
	s_nop 0
	v_pk_mul_f32 v[38:39], v[18:19], v[38:39] op_sel_hi:[0,1]
	v_pk_mul_f32 v[36:37], v[18:19], v[36:37] op_sel_hi:[0,1]
	v_pk_mul_f32 v[38:39], v[38:39], v[22:23]
	v_pk_mul_f32 v[36:37], v[36:37], v[20:21]
	global_store_dwordx4 v[4:5], v[36:39], off offset:-2048 nt
	v_pk_mul_f32 v[42:43], v[18:19], v[42:43] op_sel_hi:[0,1]
	v_pk_mul_f32 v[40:41], v[18:19], v[40:41] op_sel_hi:[0,1]
	v_pk_mul_f32 v[42:43], v[42:43], v[26:27]
	v_pk_mul_f32 v[40:41], v[40:41], v[24:25]
	global_store_dwordx4 v[4:5], v[40:43], off offset:-1024 nt
	v_pk_mul_f32 v[46:47], v[18:19], v[46:47] op_sel_hi:[0,1]
	v_pk_mul_f32 v[44:45], v[18:19], v[44:45] op_sel_hi:[0,1]
	v_pk_mul_f32 v[46:47], v[46:47], v[30:31]
	v_pk_mul_f32 v[44:45], v[44:45], v[28:29]
	global_store_dwordx4 v[4:5], v[44:47], off nt
	v_pk_mul_f32 v[50:51], v[18:19], v[50:51] op_sel_hi:[0,1]
	v_pk_mul_f32 v[48:49], v[18:19], v[48:49] op_sel_hi:[0,1]
	v_pk_mul_f32 v[50:51], v[50:51], v[34:35]
	v_pk_mul_f32 v[48:49], v[48:49], v[32:33]
	global_store_dwordx4 v[4:5], v[48:51], off offset:1024 nt
	v_lshl_add_u64 v[4:5], v[6:7], 0, s[4:5]
	s_add_i32 s28, s28, s30
	s_add_u32 s0, s0, s2
	s_addc_u32 s1, s1, s3
	s_cmp_lt_i32 s28, s98
	s_cbranch_scc0 .Lfin_B_last
	global_load_dword v18, v1, s[0:1]
	global_load_dwordx4 v[36:39], v[4:5], off offset:-2048
	global_load_dwordx4 v[40:43], v[4:5], off offset:-1024
	global_load_dwordx4 v[44:47], v[4:5], off
	global_load_dwordx4 v[48:51], v[4:5], off offset:1024
	s_waitcnt vmcnt(5)
	v_fmamk_f32 v68, v68, 0x3a800000, v0
	v_rsq_f32_e32 v68, v68
	s_nop 0
	v_pk_mul_f32 v[54:55], v[68:69], v[54:55] op_sel_hi:[0,1]
	v_pk_mul_f32 v[52:53], v[68:69], v[52:53] op_sel_hi:[0,1]
	v_pk_mul_f32 v[54:55], v[54:55], v[22:23]
	v_pk_mul_f32 v[52:53], v[52:53], v[20:21]
	global_store_dwordx4 v[6:7], v[52:55], off offset:-2048 nt
	v_pk_mul_f32 v[58:59], v[68:69], v[58:59] op_sel_hi:[0,1]
	v_pk_mul_f32 v[56:57], v[68:69], v[56:57] op_sel_hi:[0,1]
	v_pk_mul_f32 v[58:59], v[58:59], v[26:27]
	v_pk_mul_f32 v[56:57], v[56:57], v[24:25]
	global_store_dwordx4 v[6:7], v[56:59], off offset:-1024 nt
	v_pk_mul_f32 v[62:63], v[68:69], v[62:63] op_sel_hi:[0,1]
	v_pk_mul_f32 v[60:61], v[68:69], v[60:61] op_sel_hi:[0,1]
	v_pk_mul_f32 v[62:63], v[62:63], v[30:31]
	v_pk_mul_f32 v[60:61], v[60:61], v[28:29]
	global_store_dwordx4 v[6:7], v[60:63], off nt
	v_pk_mul_f32 v[66:67], v[68:69], v[66:67] op_sel_hi:[0,1]
	v_pk_mul_f32 v[64:65], v[68:69], v[64:65] op_sel_hi:[0,1]
	v_pk_mul_f32 v[66:67], v[66:67], v[34:35]
	v_pk_mul_f32 v[64:65], v[64:65], v[32:33]
	global_store_dwordx4 v[6:7], v[64:67], off offset:1024 nt
	s_branch .Lfin_A
